# hand-written grid barrier at all 6 live seams (first seam discovers per-XCC counts itself)
# speedup vs baseline: 1.0168x; 1.0007x over previous
.LBB0_40:
	s_waitcnt vmcnt(0)
	s_barrier
	s_mov_b64 s[4:5], exec
	v_readlane_b32 s0, v255, 1
	v_readlane_b32 s1, v255, 2
	s_and_b64 s[0:1], s[4:5], s[0:1]
	s_mov_b64 exec, s[0:1]
	s_cbranch_execz .Lgb1_others
	s_getreg_b32 s0, hwreg(HW_REG_XCC_ID, 0, 4)
	s_and_b32 s0, s0, 15
	s_lshl_b32 s1, s0, 8
	s_add_u32 s6, s54, s1
	s_addc_u32 s7, s55, 0
	v_mov_b32_e32 v0, 0x1000
	v_mov_b32_e32 v1, 1
	global_atomic_add v1, v0, v1, s[6:7] offset:1024 sc0
	v_readlane_b32 s1, v255, 0
	s_mul_i32 s1, s35, s1
	s_mul_i32 s15, s1, s34
	s_mov_b32 s1, 0
	v_mov_b32_e32 v0, 0x400
.Lgb1_cnt:
	global_load_dword v2, v0, s[54:55] offset:0 sc1
	global_load_dword v3, v0, s[54:55] offset:256 sc1
	global_load_dword v4, v0, s[54:55] offset:512 sc1
	global_load_dword v5, v0, s[54:55] offset:768 sc1
	global_load_dword v6, v0, s[54:55] offset:1024 sc1
	global_load_dword v7, v0, s[54:55] offset:1280 sc1
	global_load_dword v8, v0, s[54:55] offset:1536 sc1
	global_load_dword v9, v0, s[54:55] offset:1792 sc1
	global_load_dword v10, v0, s[54:55] offset:2048 sc1
	global_load_dword v11, v0, s[54:55] offset:2304 sc1
	global_load_dword v12, v0, s[54:55] offset:2560 sc1
	global_load_dword v13, v0, s[54:55] offset:2816 sc1
	global_load_dword v14, v0, s[54:55] offset:3072 sc1
	global_load_dword v15, v0, s[54:55] offset:3328 sc1
	global_load_dword v16, v0, s[54:55] offset:3584 sc1
	global_load_dword v17, v0, s[54:55] offset:3840 sc1
	s_mov_b32 s8, 0
	s_mov_b32 s9, 0
	s_mov_b32 s14, 0
	s_waitcnt vmcnt(0)
	v_readfirstlane_b32 s10, v2
	s_add_u32 s8, s8, s10
	s_cmp_eq_u32 s0, 0
	s_cselect_b32 s14, s10, s14
	s_cmp_lg_u32 s10, 0
	s_addc_u32 s9, s9, 0
	v_readfirstlane_b32 s10, v3
	s_add_u32 s8, s8, s10
	s_cmp_eq_u32 s0, 1
	s_cselect_b32 s14, s10, s14
	s_cmp_lg_u32 s10, 0
	s_addc_u32 s9, s9, 0
	v_readfirstlane_b32 s10, v4
	s_add_u32 s8, s8, s10
	s_cmp_eq_u32 s0, 2
	s_cselect_b32 s14, s10, s14
	s_cmp_lg_u32 s10, 0
	s_addc_u32 s9, s9, 0
	v_readfirstlane_b32 s10, v5
	s_add_u32 s8, s8, s10
	s_cmp_eq_u32 s0, 3
	s_cselect_b32 s14, s10, s14
	s_cmp_lg_u32 s10, 0
	s_addc_u32 s9, s9, 0
	v_readfirstlane_b32 s10, v6
	s_add_u32 s8, s8, s10
	s_cmp_eq_u32 s0, 4
	s_cselect_b32 s14, s10, s14
	s_cmp_lg_u32 s10, 0
	s_addc_u32 s9, s9, 0
	v_readfirstlane_b32 s10, v7
	s_add_u32 s8, s8, s10
	s_cmp_eq_u32 s0, 5
	s_cselect_b32 s14, s10, s14
	s_cmp_lg_u32 s10, 0
	s_addc_u32 s9, s9, 0
	v_readfirstlane_b32 s10, v8
	s_add_u32 s8, s8, s10
	s_cmp_eq_u32 s0, 6
	s_cselect_b32 s14, s10, s14
	s_cmp_lg_u32 s10, 0
	s_addc_u32 s9, s9, 0
	v_readfirstlane_b32 s10, v9
	s_add_u32 s8, s8, s10
	s_cmp_eq_u32 s0, 7
	s_cselect_b32 s14, s10, s14
	s_cmp_lg_u32 s10, 0
	s_addc_u32 s9, s9, 0
	v_readfirstlane_b32 s10, v10
	s_add_u32 s8, s8, s10
	s_cmp_eq_u32 s0, 8
	s_cselect_b32 s14, s10, s14
	s_cmp_lg_u32 s10, 0
	s_addc_u32 s9, s9, 0
	v_readfirstlane_b32 s10, v11
	s_add_u32 s8, s8, s10
	s_cmp_eq_u32 s0, 9
	s_cselect_b32 s14, s10, s14
	s_cmp_lg_u32 s10, 0
	s_addc_u32 s9, s9, 0
	v_readfirstlane_b32 s10, v12
	s_add_u32 s8, s8, s10
	s_cmp_eq_u32 s0, 10
	s_cselect_b32 s14, s10, s14
	s_cmp_lg_u32 s10, 0
	s_addc_u32 s9, s9, 0
	v_readfirstlane_b32 s10, v13
	s_add_u32 s8, s8, s10
	s_cmp_eq_u32 s0, 11
	s_cselect_b32 s14, s10, s14
	s_cmp_lg_u32 s10, 0
	s_addc_u32 s9, s9, 0
	v_readfirstlane_b32 s10, v14
	s_add_u32 s8, s8, s10
	s_cmp_eq_u32 s0, 12
	s_cselect_b32 s14, s10, s14
	s_cmp_lg_u32 s10, 0
	s_addc_u32 s9, s9, 0
	v_readfirstlane_b32 s10, v15
	s_add_u32 s8, s8, s10
	s_cmp_eq_u32 s0, 13
	s_cselect_b32 s14, s10, s14
	s_cmp_lg_u32 s10, 0
	s_addc_u32 s9, s9, 0
	v_readfirstlane_b32 s10, v16
	s_add_u32 s8, s8, s10
	s_cmp_eq_u32 s0, 14
	s_cselect_b32 s14, s10, s14
	s_cmp_lg_u32 s10, 0
	s_addc_u32 s9, s9, 0
	v_readfirstlane_b32 s10, v17
	s_add_u32 s8, s8, s10
	s_cmp_eq_u32 s0, 15
	s_cselect_b32 s14, s10, s14
	s_cmp_lg_u32 s10, 0
	s_addc_u32 s9, s9, 0
	s_cmp_eq_u32 s8, s15
	s_cbranch_scc1 .Lgb1_cntok
	s_sleep 1
	s_add_u32 s1, s1, 1
	s_cmp_lt_u32 s1, 0x40000
	s_cbranch_scc1 .Lgb1_cnt
.Lgb1_cntok:
	s_max_u32 s8, s14, 1
	s_max_u32 s9, s9, 1
	v_mov_b32_e32 v0, 0x23fc0
	v_mov_b32_e32 v2, s8
	v_mov_b32_e32 v3, s9
	ds_write_b64 v0, v[2:3]
	v_mov_b32_e32 v0, 0x3000
	s_waitcnt vmcnt(0)
	v_readfirstlane_b32 s0, v1
	s_add_u32 s0, s0, 1
	s_cmp_lg_u32 s0, s8
	s_cbranch_scc0 .Lgb1_lead
	s_branch .Lgb1_wait
.Lgb1_lead:
	buffer_wbl2 sc1
	s_waitcnt vmcnt(0)
	v_mov_b32_e32 v1, 1
	global_atomic_add v1, v0, v1, s[54:55] offset:1024 sc0
	s_waitcnt vmcnt(0)
	v_readfirstlane_b32 s0, v1
	s_add_u32 s0, s0, 1
	s_cmp_lg_u32 s0, s9
	s_cbranch_scc1 .Lgb1_wait
	v_mov_b32_e32 v1, 1
	global_atomic_add v0, v1, s[54:55] offset:1280
	s_waitcnt vmcnt(0)
	s_branch .LBB0_92

.Lgb1_spin:
	global_load_dword v1, v0, s[54:55] offset:1280 sc1
	s_waitcnt vmcnt(0)
	v_readfirstlane_b32 s0, v1
	s_cmp_ge_u32 s0, 1
	s_cbranch_scc1 .LBB0_92
	s_sleep 1
	s_add_u32 s1, s1, 1
	s_cmp_lt_u32 s1, 0x40000
	s_cbranch_scc1 .Lgb1_spin
	s_branch .LBB0_92
.Lgb1_others:
	v_readfirstlane_b32 s0, v252
	s_cmp_lg_u32 s0, 64
	s_cbranch_scc1 .LBB0_92
	s_mov_b64 exec, 1
	buffer_inv sc1
	s_waitcnt vmcnt(0)
.LBB0_92:
	s_or_b64 exec, exec, s[4:5]
	v_mov_b32_e32 v96, v252
	s_waitcnt lgkmcnt(0)
	s_barrier
	s_mov_b32 s0, 0xc000
	v_lshl_add_u32 v0, s2, 9, v96
	v_cmp_gt_i32_e32 vcc, s0, v0
	s_and_saveexec_b64 s[4:5], vcc
	s_cbranch_execz .LBB0_95
	s_add_u32 s6, s54, 0x200000
	s_addc_u32 s7, s55, 0
	s_lshl_b32 s0, s34, 9
	s_mov_b64 s[8:9], 0
	s_mov_b32 s1, 0x2aaaaaab
	s_mov_b32 s3, 0xbfff

.LBB0_132:
	s_add_u32 s12, s54, 0x200
	s_addc_u32 s13, s55, 0
	s_add_u32 s18, s54, 0x1000
	s_addc_u32 s19, s55, 0
	s_add_u32 s20, s54, 0x1100
	s_addc_u32 s21, s55, 0
	s_add_u32 s22, s54, 0x1200
	s_addc_u32 s23, s55, 0
	s_add_u32 s24, s54, 0x1300
	s_mul_i32 s83, s35, s34
	v_readlane_b32 s0, v255, 0
	s_addc_u32 s25, s55, 0
	s_mul_i32 s83, s83, s0
	s_add_u32 s0, s54, 0x3400
	s_addc_u32 s1, s55, 0
	v_writelane_b32 v255, s0, 6
	s_barrier
	s_nop 0
	v_writelane_b32 v255, s1, 7
	s_add_u32 s0, s54, 0x3500
	s_addc_u32 s1, s55, 0
	s_waitcnt vmcnt(0)
	v_writelane_b32 v255, s0, 8
	s_barrier
	s_nop 0
	v_writelane_b32 v255, s1, 9
	s_mov_b64 s[4:5], exec
	v_readlane_b32 s0, v255, 1
	v_readlane_b32 s1, v255, 2
	s_and_b64 s[0:1], s[4:5], s[0:1]
	s_mov_b64 exec, s[0:1]
	s_cbranch_execz .Lgb2_others
	s_getreg_b32 s0, hwreg(HW_REG_XCC_ID, 0, 4)
	v_mov_b32_e32 v0, 0x23fc0
	ds_read_b64 v[2:3], v0
	s_and_b32 s0, s0, 15
	s_lshl_b32 s1, s0, 8
	s_add_u32 s6, s54, s1
	s_addc_u32 s7, s55, 0
	v_mov_b32_e32 v0, 0x1000
	v_mov_b32_e32 v1, 1
	global_atomic_add v1, v0, v1, s[6:7] offset:1024 sc0
	s_waitcnt lgkmcnt(0)
	v_readfirstlane_b32 s8, v2
	v_readfirstlane_b32 s9, v3
	s_mul_i32 s8, s8, 2
	s_mul_i32 s9, s9, 2
	v_mov_b32_e32 v0, 0x3000
	s_waitcnt vmcnt(0)
	v_readfirstlane_b32 s0, v1
	s_add_u32 s0, s0, 1
	s_cmp_lg_u32 s0, s8
	s_cbranch_scc0 .Lgb2_lead
	s_branch .Lgb2_wait

.LBB0_265:
	s_waitcnt vmcnt(0)
	s_waitcnt vmcnt(0) lgkmcnt(0)
	s_barrier
	s_mov_b64 s[4:5], exec
	v_readlane_b32 s0, v255, 1
	v_readlane_b32 s1, v255, 2
	s_and_b64 s[0:1], s[4:5], s[0:1]
	s_mov_b64 exec, s[0:1]
	s_cbranch_execz .Lgb3_others
	s_getreg_b32 s0, hwreg(HW_REG_XCC_ID, 0, 4)
	v_mov_b32_e32 v0, 0x23fc0
	ds_read_b64 v[2:3], v0
	s_and_b32 s0, s0, 15
	s_lshl_b32 s1, s0, 8
	s_add_u32 s6, s54, s1
	s_addc_u32 s7, s55, 0
	v_mov_b32_e32 v0, 0x1000
	v_mov_b32_e32 v1, 1
	global_atomic_add v1, v0, v1, s[6:7] offset:1024 sc0
	s_waitcnt lgkmcnt(0)
	v_readfirstlane_b32 s8, v2
	v_readfirstlane_b32 s9, v3
	s_mul_i32 s8, s8, 3
	s_mul_i32 s9, s9, 3
	v_mov_b32_e32 v0, 0x3000
	s_waitcnt vmcnt(0)
	v_readfirstlane_b32 s0, v1
	s_add_u32 s0, s0, 1
	s_cmp_lg_u32 s0, s8
	s_cbranch_scc0 .Lgb3_lead
	s_branch .Lgb3_wait

.LBB0_618:
	s_waitcnt vmcnt(0)
	s_barrier
	s_mov_b64 s[4:5], exec
	v_readlane_b32 s0, v255, 1
	v_readlane_b32 s1, v255, 2
	s_and_b64 s[0:1], s[4:5], s[0:1]
	s_mov_b64 exec, s[0:1]
	s_cbranch_execz .Lgb4_others
	s_getreg_b32 s0, hwreg(HW_REG_XCC_ID, 0, 4)
	v_mov_b32_e32 v0, 0x23fc0
	ds_read_b64 v[2:3], v0
	s_and_b32 s0, s0, 15
	s_lshl_b32 s1, s0, 8
	s_add_u32 s6, s54, s1
	s_addc_u32 s7, s55, 0
	v_mov_b32_e32 v0, 0x1000
	v_mov_b32_e32 v1, 1
	global_atomic_add v1, v0, v1, s[6:7] offset:1024 sc0
	s_waitcnt lgkmcnt(0)
	v_readfirstlane_b32 s8, v2
	v_readfirstlane_b32 s9, v3
	s_mul_i32 s8, s8, 4
	s_mul_i32 s9, s9, 4
	v_mov_b32_e32 v0, 0x3000
	s_waitcnt vmcnt(0)
	v_readfirstlane_b32 s0, v1
	s_add_u32 s0, s0, 1
	s_cmp_lg_u32 s0, s8
	s_cbranch_scc0 .Lgb4_lead
	s_branch .Lgb4_wait

.LBB0_865:
	s_waitcnt vmcnt(0)
	s_barrier
	s_mov_b64 s[4:5], exec
	v_readlane_b32 s0, v255, 1
	v_readlane_b32 s1, v255, 2
	s_and_b64 s[0:1], s[4:5], s[0:1]
	s_mov_b64 exec, s[0:1]
	s_cbranch_execz .Lgb5_others
	s_getreg_b32 s0, hwreg(HW_REG_XCC_ID, 0, 4)
	v_mov_b32_e32 v0, 0x23fc0
	ds_read_b64 v[2:3], v0
	s_and_b32 s0, s0, 15
	s_lshl_b32 s1, s0, 8
	s_add_u32 s6, s54, s1
	s_addc_u32 s7, s55, 0
	v_mov_b32_e32 v0, 0x1000
	v_mov_b32_e32 v1, 1
	global_atomic_add v1, v0, v1, s[6:7] offset:1024 sc0
	s_waitcnt lgkmcnt(0)
	v_readfirstlane_b32 s8, v2
	v_readfirstlane_b32 s9, v3
	s_mul_i32 s8, s8, 5
	s_mul_i32 s9, s9, 5
	v_mov_b32_e32 v0, 0x3000
	s_waitcnt vmcnt(0)
	v_readfirstlane_b32 s0, v1
	s_add_u32 s0, s0, 1
	s_cmp_lg_u32 s0, s8
	s_cbranch_scc0 .Lgb5_lead
	s_branch .Lgb5_wait

.LBB0_985:
	s_waitcnt vmcnt(0)
	s_waitcnt vmcnt(0)
	s_barrier
	s_mov_b64 s[4:5], exec
	v_readlane_b32 s0, v255, 1
	v_readlane_b32 s1, v255, 2
	s_and_b64 s[0:1], s[4:5], s[0:1]
	s_mov_b64 exec, s[0:1]
	s_cbranch_execz .Lgb6_others
	s_getreg_b32 s0, hwreg(HW_REG_XCC_ID, 0, 4)
	v_mov_b32_e32 v0, 0x23fc0
	ds_read_b64 v[2:3], v0
	s_and_b32 s0, s0, 15
	s_lshl_b32 s1, s0, 8
	s_add_u32 s6, s54, s1
	s_addc_u32 s7, s55, 0
	v_mov_b32_e32 v0, 0x1000
	v_mov_b32_e32 v1, 1
	global_atomic_add v1, v0, v1, s[6:7] offset:1024 sc0
	s_waitcnt lgkmcnt(0)
	v_readfirstlane_b32 s8, v2
	v_readfirstlane_b32 s9, v3
	s_mul_i32 s8, s8, 6
	s_mul_i32 s9, s9, 6
	v_mov_b32_e32 v0, 0x3000
	s_waitcnt vmcnt(0)
	v_readfirstlane_b32 s0, v1
	s_add_u32 s0, s0, 1
	s_cmp_lg_u32 s0, s8
	s_cbranch_scc0 .Lgb6_lead
	s_branch .Lgb6_wait
